# mixers work queue: next-ticket atomic issued ~1us before item end (rglru last iteration, pool final stage, sample-attn before P.V), consumed at the fetch point
# speedup vs baseline: 1.0004x; 1.0004x over previous
.LBB0_543:
	s_or_b64 exec, exec, s[12:13]
	s_waitcnt vmcnt(0)
	v_readfirstlane_b32 s4, v238
	s_add_i32 s4, s3, s4
	s_add_i32 s4, s3, s4
	v_mov_b32_e32 v1, s53
	v_add_u32_e32 v0, s4, v0
	ds_write_b32 v1, v0

.Lq_remap:
	s_mov_b32 s32, 0
	s_cmpk_lt_i32 s81, 0x104
	s_cselect_b32 s4, 0x182, -4
	s_cmpk_lt_i32 s81, 0x286
	s_cselect_b32 s4, s4, 0
	s_add_i32 s81, s81, s4

.LBB0_618:
	s_mov_b64 s[98:99], exec
	v_readlane_b32 s100, v254, 0
	v_readlane_b32 s101, v254, 1
	s_and_b64 s[100:101], s[98:99], s[100:101]
	s_mov_b64 exec, s[100:101]
	s_cbranch_execz .Lq_pf3
	v_mov_b32_e32 v239, 1
	global_atomic_add v238, v175, v239, s[68:69] sc0
.Lq_pf3:
	s_mov_b64 exec, s[98:99]
	s_mov_b32 s32, 1
	s_lshl_b32 s10, s13, 2
	s_add_i32 s10, s10, 0
	v_mul_u32_u24_e32 v28, 0x210, v48
	v_add3_u32 v36, s10, v59, v28
	ds_read_b128 v[28:31], v36 offset:59136
	ds_read_b128 v[32:35], v36 offset:59152
	s_mov_b64 s[10:11], -1
	s_and_b64 vcc, exec, s[28:29]
	s_waitcnt lgkmcnt(1)
	v_cvt_pk_bf16_f32 v28, v28, v29
	v_cvt_pk_bf16_f32 v29, v30, v31
	s_waitcnt lgkmcnt(0)
	v_cvt_pk_bf16_f32 v30, v32, v33
	v_cvt_pk_bf16_f32 v31, v34, v35
	ds_read_b128 v[32:35], v36 offset:59264
	ds_read_b128 v[36:39], v36 offset:59280
	v_mfma_f32_16x16x32_bf16 v[12:15], v[28:31], v[12:15], 0
	s_waitcnt lgkmcnt(1)
	v_cvt_pk_bf16_f32 v32, v32, v33
	v_cvt_pk_bf16_f32 v33, v34, v35
	s_waitcnt lgkmcnt(0)
	v_cvt_pk_bf16_f32 v34, v36, v37
	v_cvt_pk_bf16_f32 v35, v38, v39
	v_mfma_f32_16x16x32_bf16 v[8:11], v[28:31], v[8:11], 0
	v_mfma_f32_16x16x32_bf16 v[12:15], v[32:35], v[0:3], v[12:15]
	v_or_b32_e32 v0, 0x70, v47
	v_mul_u32_u24_e32 v1, 0x210, v0
	v_add3_u32 v1, 0, v56, v1
	v_mfma_f32_16x16x32_bf16 v[8:11], v[32:35], v[4:7], v[8:11]
	ds_read2_b32 v[2:3], v1 offset1:132
	s_nop 2
	v_add_f32_e32 v4, v50, v12
	v_mul_f32_e32 v4, 0xbfb8aa3b, v4
	v_exp_f32_e32 v4, v4
	v_add_u32_e32 v1, 0x400, v1
	v_add_f32_e32 v5, v49, v8
	v_mul_f32_e32 v5, 0xbfb8aa3b, v5
	v_add_f32_e32 v4, 1.0, v4
	v_rcp_f32_e32 v4, v4
	v_exp_f32_e32 v5, v5
	v_mul_f32_e32 v4, v53, v4
	v_exp_f32_e32 v8, v4
	v_add_f32_e32 v5, 1.0, v5
	v_rcp_f32_e32 v5, v5
	v_fma_f32 v4, -v8, v8, 1.0
	v_max_f32_e32 v4, 0, v4
	v_sqrt_f32_e32 v4, v4
	s_waitcnt lgkmcnt(0)
	v_mul_f32_e32 v2, v2, v5
	v_add_f32_e32 v5, v49, v9
	v_mul_f32_e32 v5, 0xbfb8aa3b, v5
	v_mul_f32_e32 v4, v2, v4
	v_add_f32_e32 v2, v50, v13
	v_mul_f32_e32 v2, 0xbfb8aa3b, v2
	v_exp_f32_e32 v2, v2
	v_exp_f32_e32 v5, v5
	ds_read2_b32 v[12:13], v1 offset0:8 offset1:140
	v_add_f32_e32 v1, v50, v14
	v_add_f32_e32 v2, 1.0, v2
	v_rcp_f32_e32 v2, v2
	v_mul_f32_e32 v1, 0xbfb8aa3b, v1
	v_exp_f32_e32 v1, v1
	v_add_f32_e32 v5, 1.0, v5
	v_mul_f32_e32 v2, v53, v2
	v_exp_f32_e32 v6, v2
	v_rcp_f32_e32 v5, v5
	v_add_f32_e32 v1, 1.0, v1
	v_rcp_f32_e32 v1, v1
	v_fma_f32 v2, -v6, v6, 1.0
	v_max_f32_e32 v2, 0, v2
	v_sqrt_f32_e32 v2, v2
	v_mul_f32_e32 v3, v3, v5
	v_mul_f32_e32 v1, v53, v1
	v_exp_f32_e32 v7, v1
	v_mul_f32_e32 v3, v3, v2
	v_add_f32_e32 v2, v49, v10
	v_mul_f32_e32 v2, 0xbfb8aa3b, v2
	v_exp_f32_e32 v2, v2
	v_fma_f32 v1, -v7, v7, 1.0
	v_max_f32_e32 v1, 0, v1
	v_sqrt_f32_e32 v1, v1
	v_add_f32_e32 v2, 1.0, v2
	v_rcp_f32_e32 v2, v2
	v_add_f32_e32 v5, v49, v11
	v_mul_f32_e32 v5, 0xbfb8aa3b, v5
	v_exp_f32_e32 v5, v5
	s_waitcnt lgkmcnt(0)
	v_mul_f32_e32 v2, v12, v2
	v_mul_f32_e32 v2, v2, v1
	v_add_f32_e32 v1, v50, v15
	v_mul_f32_e32 v1, 0xbfb8aa3b, v1
	v_exp_f32_e32 v1, v1
	v_add_f32_e32 v5, 1.0, v5
	v_rcp_f32_e32 v9, v5
	v_add_f32_e32 v1, 1.0, v1
	v_rcp_f32_e32 v1, v1
	v_mul_f32_e32 v9, v13, v9
	v_mul_f32_e32 v1, v53, v1
	v_exp_f32_e32 v5, v1
	s_nop 0
	v_fma_f32 v1, -v5, v5, 1.0
	v_max_f32_e32 v1, 0, v1
	v_sqrt_f32_e32 v1, v1
	s_nop 0
	v_mul_f32_e32 v1, v9, v1
	s_cbranch_vccnz .LBB0_620
	v_or_b32_e32 v9, s12, v47
	v_add_u32_e32 v13, -16, v237
	v_and_b32_e32 v14, 64, v237
	v_or_b32_e32 v10, s40, v9
	v_fma_f32 v9, 0, v8, v4
	v_mul_f32_e32 v12, v8, v6
	v_cmp_lt_i32_e32 vcc, v13, v14
	v_fma_f32 v9, v6, v9, v3
	v_mul_f32_e32 v12, v7, v12
	v_cndmask_b32_e32 v13, v13, v237, vcc
	v_fma_f32 v9, v7, v9, v2
	v_mul_f32_e32 v12, v5, v12
	v_lshlrev_b32_e32 v13, 2, v13
	v_fma_f32 v9, v5, v9, v1
	ds_bpermute_b32 v15, v13, v12
	ds_bpermute_b32 v28, v13, v9
	v_mov_b32_e32 v11, s41
	v_lshlrev_b64 v[10:11], 10, v[10:11]
	v_lshl_add_u64 v[10:11], v[26:27], 0, v[10:11]
	s_waitcnt lgkmcnt(1)
	v_mul_f32_e32 v15, v12, v15
	s_waitcnt lgkmcnt(0)
	v_fma_f32 v28, v12, v28, v9
	v_cndmask_b32_e64 v12, v15, v12, s[22:23]
	v_subrev_u32_e32 v15, 32, v237
	v_cmp_lt_i32_e32 vcc, v15, v14
	v_cndmask_b32_e64 v9, v28, v9, s[22:23]
	v_or_b32_e32 v14, v14, v48
	v_cndmask_b32_e32 v15, v15, v237, vcc
	v_lshlrev_b32_e32 v15, 2, v15
	ds_bpermute_b32 v28, v15, v12
	ds_bpermute_b32 v15, v15, v9
	v_lshlrev_b32_e32 v14, 2, v14
	s_mov_b32 s10, 0x1c000
	v_add_co_u32_e32 v10, vcc, s10, v10
	s_waitcnt lgkmcnt(0)
	v_fma_f32 v15, v12, v15, v9
	v_mul_f32_e32 v28, v12, v28
	v_cndmask_b32_e64 v12, v12, v28, s[24:25]
	v_cndmask_b32_e64 v9, v9, v15, s[24:25]
	ds_bpermute_b32 v15, v13, v12
	ds_bpermute_b32 v13, v13, v9
	ds_bpermute_b32 v12, v14, v12 offset:192
	ds_bpermute_b32 v9, v14, v9 offset:192
	v_addc_co_u32_e32 v11, vcc, 0, v11, vcc
	s_waitcnt lgkmcnt(3)
	v_cndmask_b32_e64 v15, v15, 1.0, s[22:23]
	s_waitcnt lgkmcnt(2)
	v_cndmask_b32_e64 v13, v13, 0, s[22:23]
	v_fmac_f32_e32 v13, v45, v15
	v_mul_f32_e32 v14, v64, v15
	v_fma_f32 v13, v8, v13, v4
	v_mul_f32_e32 v14, v8, v14
	v_cvt_pk_bf16_f32 v15, v13, v14
	v_fma_f32 v13, v6, v13, v3
	global_store_dword v[10:11], v15, off
	v_mul_f32_e32 v14, v6, v14
	v_cvt_pk_bf16_f32 v15, v13, v14
	v_fma_f32 v13, v7, v13, v2
	global_store_dword v[10:11], v15, off offset:1024
	v_mul_f32_e32 v14, v7, v14
	v_cvt_pk_bf16_f32 v15, v13, v14
	v_fma_f32 v13, v5, v13, v1
	global_store_dword v[10:11], v15, off offset:2048
	v_mul_f32_e32 v14, v5, v14
	v_cvt_pk_bf16_f32 v13, v13, v14
	global_store_dword v[10:11], v13, off offset:3072
	s_waitcnt lgkmcnt(0)
	v_fmac_f32_e32 v9, v45, v12
	v_mul_f32_e32 v10, v64, v12
	s_mov_b64 s[10:11], 0

.Lq_pf2:
	s_mov_b64 exec, s[98:99]
	s_mov_b32 s32, 1
	s_cmp_lt_i32 s21, 2
	s_cselect_b64 s[10:11], -1, 0
	s_or_b64 s[10:11], s[46:47], s[10:11]
	s_andn2_b64 vcc, exec, s[10:11]
	s_waitcnt lgkmcnt(0)
	s_cbranch_vccnz .LBB0_731
	v_and_b32_e32 v11, 15, v60
	s_lshl_b32 s4, s21, 4
	s_andn2_b64 vcc, exec, s[44:45]
	s_mov_b64 s[10:11], -1
	s_cbranch_vccnz .LBB0_728
	s_lshl_b32 s10, s20, 5
	s_addk_i32 s10, 0x3000
	v_or_b32_e32 v0, s10, v11
	v_add_u32_e32 v0, s4, v0
	v_ashrrev_i32_e32 v1, 31, v0
	s_mov_b64 s[10:11], 0

.LBB0_754:
	s_or_b64 exec, exec, s[10:11]
	s_bitset1_b32 s4, 14
	s_ashr_i32 s10, s16, 6
	s_mul_i32 s12, s4, 0x600
	s_mul_hi_u32 s11, s4, 0x600
	s_add_u32 s12, s26, s12
	s_addc_u32 s13, s27, s11
	v_lshl_add_u64 v[0:1], v[8:9], 1, s[12:13]
	s_mov_b32 s11, 0x6a80000
	v_add_co_u32_e32 v0, vcc, s11, v0
	v_readlane_b32 s17, v255, 53
	s_nop 0
	v_addc_co_u32_e32 v1, vcc, 0, v1, vcc
	v_lshl_add_u32 v1, v8, 2, s17
	s_add_i32 s11, s10, 1
	v_and_b32_e32 v64, 63, v8
	v_mov_b32_e32 v0, v209
	v_lshlrev_b32_e32 v0, 16, v0
	ds_write_b32 v1, v0
	v_cvt_f32_i32_e32 v0, s11
	s_mov_b32 s11, 0x42fc0000
	s_waitcnt lgkmcnt(0)
	s_barrier
	v_cmp_lt_f32_e32 vcc, s11, v0
	s_and_b64 s[12:13], vcc, exec
	s_cselect_b32 s11, 0xffffffc0, 0
	v_cndmask_b32_e32 v1, 0, v242, vcc
	s_add_i32 s12, s10, s58
	v_sub_f32_e32 v0, v1, v0
	s_ashr_i32 s13, s12, 31
	v_exp_f32_e32 v0, v0
	s_lshl_b64 s[12:13], s[12:13], 2
	s_add_u32 s12, s22, s12
	s_addc_u32 s13, s23, s13
	global_load_dword v65, v175, s[12:13]
	s_and_b32 s12, s16, 0xffffff00
	s_and_b32 s24, s16, 0xffffffc0
	v_ldexp_f32 v0, v0, s11
	s_add_i32 s11, s12, 0
	s_lshl_b32 s13, s24, 2
	s_add_i32 s13, s17, s13
	v_mul_f32_e32 v66, 0x3fb8aa3b, v0
	v_mov_b32_e32 v0, s11
	v_mad_u32_u24 v67, v64, s72, v0
	v_mov_b32_e32 v44, s13
	ds_read_b128 v[28:31], v44
	ds_read_b128 v[8:11], v44 offset:16
	ds_read_b128 v[4:7], v44 offset:32
	ds_read_b128 v[0:3], v44 offset:48
	ds_read_b128 v[24:27], v44 offset:64
	ds_read_b128 v[16:19], v44 offset:80
	ds_read_b128 v[20:23], v44 offset:96
	ds_read_b128 v[12:15], v44 offset:112
	ds_read_b128 v[48:51], v44 offset:128
	ds_read_b128 v[32:35], v44 offset:144
	ds_read_b128 v[52:55], v44 offset:160
	ds_read_b128 v[36:39], v44 offset:176
	ds_read_b128 v[56:59], v44 offset:192
	ds_read_b128 v[40:43], v44 offset:208
	ds_read_b128 v[60:63], v44 offset:224
	ds_read_b128 v[44:47], v44 offset:240
	s_add_i32 s13, s11, 0x10800
	v_mov_b32_e32 v184, s13
	v_cmp_eq_u32_e32 vcc, 0, v64
	ds_read_b128 v[116:119], v67
	ds_read_b128 v[120:123], v67 offset:16
	ds_read_b128 v[124:127], v67 offset:32
	ds_read_b128 v[128:131], v67 offset:48
	ds_read_b128 v[132:135], v67 offset:64
	ds_read_b128 v[136:139], v67 offset:80
	ds_read_b128 v[140:143], v67 offset:96
	ds_read_b128 v[144:147], v67 offset:112
	ds_read_b128 v[148:151], v67 offset:128
	ds_read_b128 v[152:155], v67 offset:144
	ds_read_b128 v[156:159], v67 offset:160
	ds_read_b128 v[160:163], v67 offset:176
	v_sub_u32_e32 v69, 0x80, v64
	v_cvt_f32_ubyte0_e32 v69, v69
	v_or_b32_e32 v70, 64, v64
	v_sub_u32_e32 v70, 0x80, v70
	v_cvt_f32_ubyte0_e32 v70, v70
	s_waitcnt lgkmcnt(11)
	v_pk_mul_f32 v[186:187], v[28:29], v[116:117]
	v_pk_mul_f32 v[188:189], v[30:31], v[118:119]
	ds_read_b128 v[116:119], v67 offset:192
	s_waitcnt lgkmcnt(11)
	v_pk_fma_f32 v[186:187], v[8:9], v[120:121], v[186:187]
	v_pk_fma_f32 v[188:189], v[10:11], v[122:123], v[188:189]
	ds_read_b128 v[120:123], v67 offset:208
	s_waitcnt lgkmcnt(11)
	v_pk_fma_f32 v[186:187], v[4:5], v[124:125], v[186:187]
	v_pk_fma_f32 v[188:189], v[6:7], v[126:127], v[188:189]
	ds_read_b128 v[124:127], v67 offset:224
	s_waitcnt lgkmcnt(11)
	v_pk_fma_f32 v[186:187], v[0:1], v[128:129], v[186:187]
	v_pk_fma_f32 v[188:189], v[2:3], v[130:131], v[188:189]
	ds_read_b128 v[128:131], v67 offset:240
	s_waitcnt lgkmcnt(11)
	v_pk_fma_f32 v[186:187], v[24:25], v[132:133], v[186:187]
	v_pk_fma_f32 v[188:189], v[26:27], v[134:135], v[188:189]
	ds_read_b128 v[132:135], v67 offset:33792
	s_waitcnt lgkmcnt(11)
	v_pk_fma_f32 v[186:187], v[16:17], v[136:137], v[186:187]
	v_pk_fma_f32 v[188:189], v[18:19], v[138:139], v[188:189]
	ds_read_b128 v[136:139], v67 offset:33808
	s_waitcnt lgkmcnt(11)
	v_pk_fma_f32 v[186:187], v[20:21], v[140:141], v[186:187]
	v_pk_fma_f32 v[188:189], v[22:23], v[142:143], v[188:189]
	ds_read_b128 v[140:143], v67 offset:33824
	s_waitcnt lgkmcnt(11)
	v_pk_fma_f32 v[186:187], v[12:13], v[144:145], v[186:187]
	v_pk_fma_f32 v[188:189], v[14:15], v[146:147], v[188:189]
	ds_read_b128 v[144:147], v67 offset:33840
	s_waitcnt lgkmcnt(11)
	v_pk_fma_f32 v[186:187], v[48:49], v[148:149], v[186:187]
	v_pk_fma_f32 v[188:189], v[50:51], v[150:151], v[188:189]
	ds_read_b128 v[148:151], v67 offset:33856
	s_waitcnt lgkmcnt(11)
	v_pk_fma_f32 v[186:187], v[32:33], v[152:153], v[186:187]
	v_pk_fma_f32 v[188:189], v[34:35], v[154:155], v[188:189]
	ds_read_b128 v[152:155], v67 offset:33872
	s_waitcnt lgkmcnt(11)
	v_pk_fma_f32 v[186:187], v[52:53], v[156:157], v[186:187]
	v_pk_fma_f32 v[188:189], v[54:55], v[158:159], v[188:189]
	ds_read_b128 v[156:159], v67 offset:33888
	s_waitcnt lgkmcnt(11)
	v_pk_fma_f32 v[186:187], v[36:37], v[160:161], v[186:187]
	v_pk_fma_f32 v[188:189], v[38:39], v[162:163], v[188:189]
	ds_read_b128 v[160:163], v67 offset:33904
	s_waitcnt lgkmcnt(11)
	v_pk_fma_f32 v[186:187], v[56:57], v[116:117], v[186:187]
	v_pk_fma_f32 v[188:189], v[58:59], v[118:119], v[188:189]
	ds_read_b128 v[116:119], v67 offset:33920
	s_waitcnt lgkmcnt(11)
	v_pk_fma_f32 v[186:187], v[40:41], v[120:121], v[186:187]
	v_pk_fma_f32 v[188:189], v[42:43], v[122:123], v[188:189]
	ds_read_b128 v[120:123], v67 offset:33936
	s_waitcnt lgkmcnt(11)
	v_pk_fma_f32 v[186:187], v[60:61], v[124:125], v[186:187]
	v_pk_fma_f32 v[188:189], v[62:63], v[126:127], v[188:189]
	ds_read_b128 v[124:127], v67 offset:33952
	s_waitcnt lgkmcnt(11)
	v_pk_fma_f32 v[186:187], v[44:45], v[128:129], v[186:187]
	v_pk_fma_f32 v[188:189], v[46:47], v[130:131], v[188:189]
	ds_read_b128 v[128:131], v67 offset:33968
	s_waitcnt lgkmcnt(11)
	v_pk_mul_f32 v[190:191], v[28:29], v[132:133]
	v_pk_mul_f32 v[192:193], v[30:31], v[134:135]
	ds_read_b128 v[132:135], v67 offset:33984
	s_waitcnt lgkmcnt(11)
	v_pk_fma_f32 v[190:191], v[8:9], v[136:137], v[190:191]
	v_pk_fma_f32 v[192:193], v[10:11], v[138:139], v[192:193]
	ds_read_b128 v[136:139], v67 offset:34000
	s_waitcnt lgkmcnt(11)
	v_pk_fma_f32 v[190:191], v[4:5], v[140:141], v[190:191]
	v_pk_fma_f32 v[192:193], v[6:7], v[142:143], v[192:193]
	ds_read_b128 v[140:143], v67 offset:34016
	s_waitcnt lgkmcnt(11)
	v_pk_fma_f32 v[190:191], v[0:1], v[144:145], v[190:191]
	v_pk_fma_f32 v[192:193], v[2:3], v[146:147], v[192:193]
	ds_read_b128 v[144:147], v67 offset:34032
	s_waitcnt lgkmcnt(11)
	v_pk_fma_f32 v[190:191], v[24:25], v[148:149], v[190:191]
	v_pk_fma_f32 v[192:193], v[26:27], v[150:151], v[192:193]
	ds_read_b128 v[148:151], v184
	s_waitcnt lgkmcnt(11)
	v_pk_fma_f32 v[190:191], v[16:17], v[152:153], v[190:191]
	v_pk_fma_f32 v[192:193], v[18:19], v[154:155], v[192:193]
	ds_read_b128 v[152:155], v184 offset:16
	s_waitcnt lgkmcnt(11)
	v_pk_fma_f32 v[190:191], v[20:21], v[156:157], v[190:191]
	v_pk_fma_f32 v[192:193], v[22:23], v[158:159], v[192:193]
	ds_read_b128 v[156:159], v184 offset:32
	s_waitcnt lgkmcnt(11)
	v_pk_fma_f32 v[190:191], v[12:13], v[160:161], v[190:191]
	v_pk_fma_f32 v[192:193], v[14:15], v[162:163], v[192:193]
	ds_read_b128 v[160:163], v184 offset:48
	s_waitcnt lgkmcnt(11)
	v_pk_fma_f32 v[190:191], v[48:49], v[116:117], v[190:191]
	v_pk_fma_f32 v[192:193], v[50:51], v[118:119], v[192:193]
	ds_read_b128 v[116:119], v184 offset:64
	s_waitcnt lgkmcnt(11)
	v_pk_fma_f32 v[190:191], v[32:33], v[120:121], v[190:191]
	v_pk_fma_f32 v[192:193], v[34:35], v[122:123], v[192:193]
	ds_read_b128 v[120:123], v184 offset:80
	s_waitcnt lgkmcnt(11)
	v_pk_fma_f32 v[190:191], v[52:53], v[124:125], v[190:191]
	v_pk_fma_f32 v[192:193], v[54:55], v[126:127], v[192:193]
	ds_read_b128 v[124:127], v184 offset:96
	s_waitcnt lgkmcnt(11)
	v_pk_fma_f32 v[190:191], v[36:37], v[128:129], v[190:191]
	v_pk_fma_f32 v[192:193], v[38:39], v[130:131], v[192:193]
	ds_read_b128 v[128:131], v184 offset:112
	s_waitcnt lgkmcnt(11)
	v_pk_fma_f32 v[190:191], v[56:57], v[132:133], v[190:191]
	v_pk_fma_f32 v[192:193], v[58:59], v[134:135], v[192:193]
	ds_read_b128 v[132:135], v184 offset:128
	s_waitcnt lgkmcnt(11)
	v_pk_fma_f32 v[190:191], v[40:41], v[136:137], v[190:191]
	v_pk_fma_f32 v[192:193], v[42:43], v[138:139], v[192:193]
	ds_read_b128 v[136:139], v184 offset:144
	s_waitcnt lgkmcnt(11)
	v_pk_fma_f32 v[190:191], v[60:61], v[140:141], v[190:191]
	v_pk_fma_f32 v[192:193], v[62:63], v[142:143], v[192:193]
	ds_read_b128 v[140:143], v184 offset:160
	s_waitcnt lgkmcnt(11)
	v_pk_fma_f32 v[190:191], v[44:45], v[144:145], v[190:191]
	v_pk_fma_f32 v[192:193], v[46:47], v[146:147], v[192:193]
	ds_read_b128 v[144:147], v184 offset:176
	s_waitcnt lgkmcnt(11)
	v_pk_mul_f32 v[194:195], v[28:29], v[148:149]
	v_pk_mul_f32 v[196:197], v[30:31], v[150:151]
	ds_read_b128 v[148:151], v184 offset:192
	s_waitcnt lgkmcnt(11)
	v_pk_fma_f32 v[194:195], v[8:9], v[152:153], v[194:195]
	v_pk_fma_f32 v[196:197], v[10:11], v[154:155], v[196:197]
	ds_read_b128 v[152:155], v184 offset:208
	s_waitcnt lgkmcnt(11)
	v_pk_fma_f32 v[194:195], v[4:5], v[156:157], v[194:195]
	v_pk_fma_f32 v[196:197], v[6:7], v[158:159], v[196:197]
	ds_read_b128 v[156:159], v184 offset:224
	s_waitcnt lgkmcnt(11)
	v_pk_fma_f32 v[194:195], v[0:1], v[160:161], v[194:195]
	v_pk_fma_f32 v[196:197], v[2:3], v[162:163], v[196:197]
	ds_read_b128 v[160:163], v184 offset:240
	s_waitcnt lgkmcnt(11)
	v_pk_fma_f32 v[194:195], v[24:25], v[116:117], v[194:195]
	v_pk_fma_f32 v[196:197], v[26:27], v[118:119], v[196:197]
	s_waitcnt lgkmcnt(10)
	v_pk_fma_f32 v[194:195], v[16:17], v[120:121], v[194:195]
	v_pk_fma_f32 v[196:197], v[18:19], v[122:123], v[196:197]
	s_waitcnt lgkmcnt(9)
	v_pk_fma_f32 v[194:195], v[20:21], v[124:125], v[194:195]
	v_pk_fma_f32 v[196:197], v[22:23], v[126:127], v[196:197]
	s_waitcnt lgkmcnt(8)
	v_pk_fma_f32 v[194:195], v[12:13], v[128:129], v[194:195]
	v_pk_fma_f32 v[196:197], v[14:15], v[130:131], v[196:197]
	s_waitcnt lgkmcnt(7)
	v_pk_fma_f32 v[194:195], v[48:49], v[132:133], v[194:195]
	v_pk_fma_f32 v[196:197], v[50:51], v[134:135], v[196:197]
	s_waitcnt lgkmcnt(6)
	v_pk_fma_f32 v[194:195], v[32:33], v[136:137], v[194:195]
	v_pk_fma_f32 v[196:197], v[34:35], v[138:139], v[196:197]
	s_waitcnt lgkmcnt(5)
	v_pk_fma_f32 v[194:195], v[52:53], v[140:141], v[194:195]
	v_pk_fma_f32 v[196:197], v[54:55], v[142:143], v[196:197]
	s_waitcnt lgkmcnt(4)
	v_pk_fma_f32 v[194:195], v[36:37], v[144:145], v[194:195]
	v_pk_fma_f32 v[196:197], v[38:39], v[146:147], v[196:197]
	s_waitcnt lgkmcnt(3)
	v_pk_fma_f32 v[194:195], v[56:57], v[148:149], v[194:195]
	v_pk_fma_f32 v[196:197], v[58:59], v[150:151], v[196:197]
	s_waitcnt lgkmcnt(2)
	v_pk_fma_f32 v[194:195], v[40:41], v[152:153], v[194:195]
	v_pk_fma_f32 v[196:197], v[42:43], v[154:155], v[196:197]
	s_waitcnt lgkmcnt(1)
	v_pk_fma_f32 v[194:195], v[60:61], v[156:157], v[194:195]
	v_pk_fma_f32 v[196:197], v[62:63], v[158:159], v[196:197]
	s_waitcnt lgkmcnt(0)
	v_pk_fma_f32 v[194:195], v[44:45], v[160:161], v[194:195]
	v_pk_fma_f32 v[196:197], v[46:47], v[162:163], v[196:197]
	v_add_f32_e32 v186, v186, v187
	v_add_f32_e32 v188, v188, v189
	v_add_f32_e32 v68, v186, v188
	v_add_f32_e32 v190, v190, v191
	v_add_f32_e32 v192, v192, v193
	v_add_f32_e32 v67, v190, v192
	v_add_f32_e32 v194, v194, v195
	v_add_f32_e32 v196, v196, v197
	v_add_f32_e32 v71, v194, v196
	v_fma_f32 v68, -v66, v69, v68
	v_fma_f32 v67, -v66, v70, v67
	s_mul_i32 s13, s10, 0x210
	s_add_i32 s16, s13, 0
	s_add_i32 s16, s16, 0x21420
	v_mov_b32_e32 v0, v71
	v_fmac_f32_e32 v0, 0x80000000, v66
	v_cndmask_b32_e32 v2, v243, v0, vcc
	s_waitcnt vmcnt(0)
	v_mul_f32_e32 v0, 0x3fb8aa3b, v65
	v_max_f32_e32 v1, v2, v0
	v_max3_f32 v1, v68, v67, v1
	s_nop 1
	v_max_f32_dpp v1, v1, v1 quad_perm:[1,0,3,2] row_mask:0xf bank_mask:0xf
	s_nop 1
	v_max_f32_dpp v1, v1, v1 quad_perm:[2,3,0,1] row_mask:0xf bank_mask:0xf
	s_nop 1
	v_max_f32_dpp v1, v1, v1 row_half_mirror row_mask:0xf bank_mask:0xf
	s_nop 1
	v_max_f32_dpp v1, v1, v1 row_mirror row_mask:0xf bank_mask:0xf
	s_nop 1
	v_readlane_b32 s20, v1, 0
	v_readlane_b32 s21, v1, 16
	v_readlane_b32 s40, v1, 32
	v_readlane_b32 s41, v1, 48
	v_mov_b32_e32 v4, s20
	v_max_f32_e32 v4, s21, v4
	v_max_f32_e32 v4, s40, v4
	v_max_f32_e32 v1, s41, v4
	v_sub_f32_e32 v4, v68, v1
	v_exp_f32_e32 v10, v4
	v_sub_f32_e32 v11, v67, v1
	v_exp_f32_e32 v11, v11
	v_sub_f32_e32 v2, v2, v1
	v_add_f32_e32 v4, 0, v10
	v_add_f32_e32 v12, v11, v4
	v_exp_f32_e32 v4, v2
	s_nop 0
	v_add_f32_e32 v2, v4, v12
	s_nop 1
	v_add_f32_dpp v2, v2, v2 quad_perm:[1,0,3,2] row_mask:0xf bank_mask:0xf
	s_nop 1
	v_add_f32_dpp v2, v2, v2 quad_perm:[2,3,0,1] row_mask:0xf bank_mask:0xf
	s_nop 1
	v_add_f32_dpp v2, v2, v2 row_half_mirror row_mask:0xf bank_mask:0xf
	s_nop 1
	v_add_f32_dpp v2, v2, v2 row_mirror row_mask:0xf bank_mask:0xf
	s_nop 1
	v_readlane_b32 s20, v2, 0
	v_readlane_b32 s21, v2, 16
	v_readlane_b32 s40, v2, 32
	v_readlane_b32 s41, v2, 48
	v_mov_b32_e32 v3, s20
	v_add_f32_e32 v3, s21, v3
	v_add_f32_e32 v3, s40, v3
	v_add_f32_e32 v2, s41, v3
	v_mov_b32_e32 v3, 0
	v_lshl_add_u32 v5, v64, 2, s16
	ds_write2st64_b32 v5, v10, v11 offset1:1
	s_and_saveexec_b64 s[10:11], vcc
	v_mov_b32_e32 v5, s16
	ds_write_b32 v5, v4 offset:512
	s_or_b64 exec, exec, s[10:11]
	s_waitcnt lgkmcnt(0)
	s_mov_b64 s[98:99], exec
	v_readlane_b32 s100, v254, 0
	v_readlane_b32 s101, v254, 1
	s_and_b64 s[100:101], s[98:99], s[100:101]
	s_mov_b64 exec, s[100:101]
	s_cbranch_execz .Lq_pf1
	v_mov_b32_e32 v239, 1
	global_atomic_add v238, v175, v239, s[68:69] sc0
.Lq_pf1:
	s_mov_b64 exec, s[98:99]
	s_mov_b32 s32, 1
	s_add_i32 s10, s12, 0x10a10
	v_lshlrev_b32_e32 v149, 2, v64
	v_add_u32_e32 v149, s10, v149
	v_add_u32_e32 v150, 0x400, v149
	v_add_u32_e32 v151, 0x800, v149
	v_add_u32_e32 v152, 0xc00, v149
	s_add_i32 s11, s13, 0x21420
	v_mov_b32_e32 v148, s11
	v_mov_b32_e32 v4, 0
	ds_read_b128 v[116:119], v148
	ds_read_b128 v[120:123], v148 offset:16
	ds_read2_b32 v[124:125], v149 offset1:132
	ds_read2_b32 v[126:127], v150 offset0:8 offset1:140
	ds_read2_b32 v[128:129], v151 offset0:16 offset1:148
	ds_read2_b32 v[130:131], v152 offset0:24 offset1:156
	v_add_u32_e32 v149, 0x1080, v149
	v_add_u32_e32 v150, 0x1080, v150
	v_add_u32_e32 v151, 0x1080, v151
	v_add_u32_e32 v152, 0x1080, v152
	ds_read_b128 v[132:135], v148 offset:32
	ds_read_b128 v[136:139], v148 offset:48
	ds_read2_b32 v[140:141], v149 offset1:132
	ds_read2_b32 v[142:143], v150 offset0:8 offset1:140
	ds_read2_b32 v[144:145], v151 offset0:16 offset1:148
	ds_read2_b32 v[146:147], v152 offset0:24 offset1:156
	v_add_u32_e32 v149, 0x1080, v149
	v_add_u32_e32 v150, 0x1080, v150
	v_add_u32_e32 v151, 0x1080, v151
	v_add_u32_e32 v152, 0x1080, v152
	s_waitcnt lgkmcnt(6)
	v_fmac_f32_e32 v4, v116, v124
	v_fmac_f32_e32 v4, v117, v125
	v_fmac_f32_e32 v4, v118, v126
	v_fmac_f32_e32 v4, v119, v127
	v_fmac_f32_e32 v4, v120, v128
	v_fmac_f32_e32 v4, v121, v129
	v_fmac_f32_e32 v4, v122, v130
	v_fmac_f32_e32 v4, v123, v131
	ds_read_b128 v[116:119], v148 offset:64
	ds_read_b128 v[120:123], v148 offset:80
	ds_read2_b32 v[124:125], v149 offset1:132
	ds_read2_b32 v[126:127], v150 offset0:8 offset1:140
	ds_read2_b32 v[128:129], v151 offset0:16 offset1:148
	ds_read2_b32 v[130:131], v152 offset0:24 offset1:156
	v_add_u32_e32 v149, 0x1080, v149
	v_add_u32_e32 v150, 0x1080, v150
	v_add_u32_e32 v151, 0x1080, v151
	v_add_u32_e32 v152, 0x1080, v152
	s_waitcnt lgkmcnt(6)
	v_fmac_f32_e32 v4, v132, v140
	v_fmac_f32_e32 v4, v133, v141
	v_fmac_f32_e32 v4, v134, v142
	v_fmac_f32_e32 v4, v135, v143
	v_fmac_f32_e32 v4, v136, v144
	v_fmac_f32_e32 v4, v137, v145
	v_fmac_f32_e32 v4, v138, v146
	v_fmac_f32_e32 v4, v139, v147
	ds_read_b128 v[132:135], v148 offset:96
	ds_read_b128 v[136:139], v148 offset:112
	ds_read2_b32 v[140:141], v149 offset1:132
	ds_read2_b32 v[142:143], v150 offset0:8 offset1:140
	ds_read2_b32 v[144:145], v151 offset0:16 offset1:148
	ds_read2_b32 v[146:147], v152 offset0:24 offset1:156
	v_add_u32_e32 v149, 0x1080, v149
	v_add_u32_e32 v150, 0x1080, v150
	v_add_u32_e32 v151, 0x1080, v151
	v_add_u32_e32 v152, 0x1080, v152
	s_waitcnt lgkmcnt(6)
	v_fmac_f32_e32 v4, v116, v124
	v_fmac_f32_e32 v4, v117, v125
	v_fmac_f32_e32 v4, v118, v126
	v_fmac_f32_e32 v4, v119, v127
	v_fmac_f32_e32 v4, v120, v128
	v_fmac_f32_e32 v4, v121, v129
	v_fmac_f32_e32 v4, v122, v130
	v_fmac_f32_e32 v4, v123, v131
	ds_read_b128 v[116:119], v148 offset:128
	ds_read_b128 v[120:123], v148 offset:144
	ds_read2_b32 v[124:125], v149 offset1:132
	ds_read2_b32 v[126:127], v150 offset0:8 offset1:140
	ds_read2_b32 v[128:129], v151 offset0:16 offset1:148
	ds_read2_b32 v[130:131], v152 offset0:24 offset1:156
	v_add_u32_e32 v149, 0x1080, v149
	v_add_u32_e32 v150, 0x1080, v150
	v_add_u32_e32 v151, 0x1080, v151
	v_add_u32_e32 v152, 0x1080, v152
	s_waitcnt lgkmcnt(6)
	v_fmac_f32_e32 v4, v132, v140
	v_fmac_f32_e32 v4, v133, v141
	v_fmac_f32_e32 v4, v134, v142
	v_fmac_f32_e32 v4, v135, v143
	v_fmac_f32_e32 v4, v136, v144
	v_fmac_f32_e32 v4, v137, v145
	v_fmac_f32_e32 v4, v138, v146
	v_fmac_f32_e32 v4, v139, v147
	ds_read_b128 v[132:135], v148 offset:160
	ds_read_b128 v[136:139], v148 offset:176
	ds_read2_b32 v[140:141], v149 offset1:132
	ds_read2_b32 v[142:143], v150 offset0:8 offset1:140
	ds_read2_b32 v[144:145], v151 offset0:16 offset1:148
	ds_read2_b32 v[146:147], v152 offset0:24 offset1:156
	v_add_u32_e32 v149, 0x1080, v149
	v_add_u32_e32 v150, 0x1080, v150
	v_add_u32_e32 v151, 0x1080, v151
	v_add_u32_e32 v152, 0x1080, v152
	s_waitcnt lgkmcnt(6)
	v_fmac_f32_e32 v4, v116, v124
	v_fmac_f32_e32 v4, v117, v125
	v_fmac_f32_e32 v4, v118, v126
	v_fmac_f32_e32 v4, v119, v127
	v_fmac_f32_e32 v4, v120, v128
	v_fmac_f32_e32 v4, v121, v129
	v_fmac_f32_e32 v4, v122, v130
	v_fmac_f32_e32 v4, v123, v131
	ds_read_b128 v[116:119], v148 offset:192
	ds_read_b128 v[120:123], v148 offset:208
	ds_read2_b32 v[124:125], v149 offset1:132
	ds_read2_b32 v[126:127], v150 offset0:8 offset1:140
	ds_read2_b32 v[128:129], v151 offset0:16 offset1:148
	ds_read2_b32 v[130:131], v152 offset0:24 offset1:156
	v_add_u32_e32 v149, 0x1080, v149
	v_add_u32_e32 v150, 0x1080, v150
	v_add_u32_e32 v151, 0x1080, v151
	v_add_u32_e32 v152, 0x1080, v152
	s_waitcnt lgkmcnt(6)
	v_fmac_f32_e32 v4, v132, v140
	v_fmac_f32_e32 v4, v133, v141
	v_fmac_f32_e32 v4, v134, v142
	v_fmac_f32_e32 v4, v135, v143
	v_fmac_f32_e32 v4, v136, v144
	v_fmac_f32_e32 v4, v137, v145
	v_fmac_f32_e32 v4, v138, v146
	v_fmac_f32_e32 v4, v139, v147
	ds_read_b128 v[132:135], v148 offset:224
	ds_read_b128 v[136:139], v148 offset:240
	ds_read2_b32 v[140:141], v149 offset1:132
	ds_read2_b32 v[142:143], v150 offset0:8 offset1:140
	ds_read2_b32 v[144:145], v151 offset0:16 offset1:148
	ds_read2_b32 v[146:147], v152 offset0:24 offset1:156
	v_add_u32_e32 v149, 0x1080, v149
	v_add_u32_e32 v150, 0x1080, v150
	v_add_u32_e32 v151, 0x1080, v151
	v_add_u32_e32 v152, 0x1080, v152
	s_waitcnt lgkmcnt(6)
	v_fmac_f32_e32 v4, v116, v124
	v_fmac_f32_e32 v4, v117, v125
	v_fmac_f32_e32 v4, v118, v126
	v_fmac_f32_e32 v4, v119, v127
	v_fmac_f32_e32 v4, v120, v128
	v_fmac_f32_e32 v4, v121, v129
	v_fmac_f32_e32 v4, v122, v130
	v_fmac_f32_e32 v4, v123, v131
	ds_read_b128 v[116:119], v148 offset:256
	ds_read_b128 v[120:123], v148 offset:272
	ds_read2_b32 v[124:125], v149 offset1:132
	ds_read2_b32 v[126:127], v150 offset0:8 offset1:140
	ds_read2_b32 v[128:129], v151 offset0:16 offset1:148
	ds_read2_b32 v[130:131], v152 offset0:24 offset1:156
	v_add_u32_e32 v149, 0x1080, v149
	v_add_u32_e32 v150, 0x1080, v150
	v_add_u32_e32 v151, 0x1080, v151
	v_add_u32_e32 v152, 0x1080, v152
	s_waitcnt lgkmcnt(6)
	v_fmac_f32_e32 v4, v132, v140
	v_fmac_f32_e32 v4, v133, v141
	v_fmac_f32_e32 v4, v134, v142
	v_fmac_f32_e32 v4, v135, v143
	v_fmac_f32_e32 v4, v136, v144
	v_fmac_f32_e32 v4, v137, v145
	v_fmac_f32_e32 v4, v138, v146
	v_fmac_f32_e32 v4, v139, v147
	ds_read_b128 v[132:135], v148 offset:288
	ds_read_b128 v[136:139], v148 offset:304
	ds_read2_b32 v[140:141], v149 offset1:132
	ds_read2_b32 v[142:143], v150 offset0:8 offset1:140
	ds_read2_b32 v[144:145], v151 offset0:16 offset1:148
	ds_read2_b32 v[146:147], v152 offset0:24 offset1:156
	v_add_u32_e32 v149, 0x1080, v149
	v_add_u32_e32 v150, 0x1080, v150
	v_add_u32_e32 v151, 0x1080, v151
	v_add_u32_e32 v152, 0x1080, v152
	s_waitcnt lgkmcnt(6)
	v_fmac_f32_e32 v4, v116, v124
	v_fmac_f32_e32 v4, v117, v125
	v_fmac_f32_e32 v4, v118, v126
	v_fmac_f32_e32 v4, v119, v127
	v_fmac_f32_e32 v4, v120, v128
	v_fmac_f32_e32 v4, v121, v129
	v_fmac_f32_e32 v4, v122, v130
	v_fmac_f32_e32 v4, v123, v131
	ds_read_b128 v[116:119], v148 offset:320
	ds_read_b128 v[120:123], v148 offset:336
	ds_read2_b32 v[124:125], v149 offset1:132
	ds_read2_b32 v[126:127], v150 offset0:8 offset1:140
	ds_read2_b32 v[128:129], v151 offset0:16 offset1:148
	ds_read2_b32 v[130:131], v152 offset0:24 offset1:156
	v_add_u32_e32 v149, 0x1080, v149
	v_add_u32_e32 v150, 0x1080, v150
	v_add_u32_e32 v151, 0x1080, v151
	v_add_u32_e32 v152, 0x1080, v152
	s_waitcnt lgkmcnt(6)
	v_fmac_f32_e32 v4, v132, v140
	v_fmac_f32_e32 v4, v133, v141
	v_fmac_f32_e32 v4, v134, v142
	v_fmac_f32_e32 v4, v135, v143
	v_fmac_f32_e32 v4, v136, v144
	v_fmac_f32_e32 v4, v137, v145
	v_fmac_f32_e32 v4, v138, v146
	v_fmac_f32_e32 v4, v139, v147
	ds_read_b128 v[132:135], v148 offset:352
	ds_read_b128 v[136:139], v148 offset:368
	ds_read2_b32 v[140:141], v149 offset1:132
	ds_read2_b32 v[142:143], v150 offset0:8 offset1:140
	ds_read2_b32 v[144:145], v151 offset0:16 offset1:148
	ds_read2_b32 v[146:147], v152 offset0:24 offset1:156
	v_add_u32_e32 v149, 0x1080, v149
	v_add_u32_e32 v150, 0x1080, v150
	v_add_u32_e32 v151, 0x1080, v151
	v_add_u32_e32 v152, 0x1080, v152
	s_waitcnt lgkmcnt(6)
	v_fmac_f32_e32 v4, v116, v124
	v_fmac_f32_e32 v4, v117, v125
	v_fmac_f32_e32 v4, v118, v126
	v_fmac_f32_e32 v4, v119, v127
	v_fmac_f32_e32 v4, v120, v128
	v_fmac_f32_e32 v4, v121, v129
	v_fmac_f32_e32 v4, v122, v130
	v_fmac_f32_e32 v4, v123, v131
	ds_read_b128 v[116:119], v148 offset:384
	ds_read_b128 v[120:123], v148 offset:400
	ds_read2_b32 v[124:125], v149 offset1:132
	ds_read2_b32 v[126:127], v150 offset0:8 offset1:140
	ds_read2_b32 v[128:129], v151 offset0:16 offset1:148
	ds_read2_b32 v[130:131], v152 offset0:24 offset1:156
	v_add_u32_e32 v149, 0x1080, v149
	v_add_u32_e32 v150, 0x1080, v150
	v_add_u32_e32 v151, 0x1080, v151
	v_add_u32_e32 v152, 0x1080, v152
	s_waitcnt lgkmcnt(6)
	v_fmac_f32_e32 v4, v132, v140
	v_fmac_f32_e32 v4, v133, v141
	v_fmac_f32_e32 v4, v134, v142
	v_fmac_f32_e32 v4, v135, v143
	v_fmac_f32_e32 v4, v136, v144
	v_fmac_f32_e32 v4, v137, v145
	v_fmac_f32_e32 v4, v138, v146
	v_fmac_f32_e32 v4, v139, v147
	ds_read_b128 v[132:135], v148 offset:416
	ds_read_b128 v[136:139], v148 offset:432
	ds_read2_b32 v[140:141], v149 offset1:132
	ds_read2_b32 v[142:143], v150 offset0:8 offset1:140
	ds_read2_b32 v[144:145], v151 offset0:16 offset1:148
	ds_read2_b32 v[146:147], v152 offset0:24 offset1:156
	v_add_u32_e32 v149, 0x1080, v149
	v_add_u32_e32 v150, 0x1080, v150
	v_add_u32_e32 v151, 0x1080, v151
	v_add_u32_e32 v152, 0x1080, v152
	s_waitcnt lgkmcnt(6)
	v_fmac_f32_e32 v4, v116, v124
	v_fmac_f32_e32 v4, v117, v125
	v_fmac_f32_e32 v4, v118, v126
	v_fmac_f32_e32 v4, v119, v127
	v_fmac_f32_e32 v4, v120, v128
	v_fmac_f32_e32 v4, v121, v129
	v_fmac_f32_e32 v4, v122, v130
	v_fmac_f32_e32 v4, v123, v131
	ds_read_b128 v[116:119], v148 offset:448
	ds_read_b128 v[120:123], v148 offset:464
	ds_read2_b32 v[124:125], v149 offset1:132
	ds_read2_b32 v[126:127], v150 offset0:8 offset1:140
	ds_read2_b32 v[128:129], v151 offset0:16 offset1:148
	ds_read2_b32 v[130:131], v152 offset0:24 offset1:156
	v_add_u32_e32 v149, 0x1080, v149
	v_add_u32_e32 v150, 0x1080, v150
	v_add_u32_e32 v151, 0x1080, v151
	v_add_u32_e32 v152, 0x1080, v152
	s_waitcnt lgkmcnt(6)
	v_fmac_f32_e32 v4, v132, v140
	v_fmac_f32_e32 v4, v133, v141
	v_fmac_f32_e32 v4, v134, v142
	v_fmac_f32_e32 v4, v135, v143
	v_fmac_f32_e32 v4, v136, v144
	v_fmac_f32_e32 v4, v137, v145
	v_fmac_f32_e32 v4, v138, v146
	v_fmac_f32_e32 v4, v139, v147
	ds_read_b128 v[132:135], v148 offset:480
	ds_read_b128 v[136:139], v148 offset:496
	ds_read2_b32 v[140:141], v149 offset1:132
	ds_read2_b32 v[142:143], v150 offset0:8 offset1:140
	ds_read2_b32 v[144:145], v151 offset0:16 offset1:148
	ds_read2_b32 v[146:147], v152 offset0:24 offset1:156
	v_add_u32_e32 v149, 0x1080, v149
	v_add_u32_e32 v150, 0x1080, v150
	v_add_u32_e32 v151, 0x1080, v151
	v_add_u32_e32 v152, 0x1080, v152
	s_waitcnt lgkmcnt(6)
	v_fmac_f32_e32 v4, v116, v124
	v_fmac_f32_e32 v4, v117, v125
	v_fmac_f32_e32 v4, v118, v126
	v_fmac_f32_e32 v4, v119, v127
	v_fmac_f32_e32 v4, v120, v128
	v_fmac_f32_e32 v4, v121, v129
	v_fmac_f32_e32 v4, v122, v130
	v_fmac_f32_e32 v4, v123, v131
	ds_read_b32 v153, v148 offset:512
	ds_read_b32 v154, v149
	s_waitcnt lgkmcnt(2)
	v_fmac_f32_e32 v4, v132, v140
	v_fmac_f32_e32 v4, v133, v141
	v_fmac_f32_e32 v4, v134, v142
	v_fmac_f32_e32 v4, v135, v143
	v_fmac_f32_e32 v4, v136, v144
	v_fmac_f32_e32 v4, v137, v145
	v_fmac_f32_e32 v4, v138, v146
	v_fmac_f32_e32 v4, v139, v147
	s_waitcnt lgkmcnt(0)
	v_fmac_f32_e32 v4, v153, v154

.LBB0_761:
	s_mov_b64 s[10:11], exec
	v_readlane_b32 s12, v254, 0
	v_readlane_b32 s13, v254, 1
	s_and_b64 s[12:13], s[10:11], s[12:13]
	s_mov_b64 exec, s[12:13]
	s_cbranch_execz .LBB0_544
	s_mov_b64 s[16:17], exec
	s_waitcnt vmcnt(7)
	v_mbcnt_lo_u32_b32 v0, s16, 0
	v_mbcnt_hi_u32_b32 v0, s17, v0
	v_cmp_eq_u32_e32 vcc, 0, v0
	s_and_saveexec_b64 s[12:13], vcc
	s_cbranch_execz .LBB0_543
	s_cmp_eq_u32 s32, 1
	s_cbranch_scc1 .LBB0_543
	s_bcnt1_i32_b64 s4, s[16:17]
	v_mov_b32_e32 v239, s4
	global_atomic_add v238, v175, v239, s[68:69] sc0
	s_branch .LBB0_543
